# pp_v14 + RC1 S4 output tiles: all operand LDS reads of both row halves issued up front (shared A read once), MFMA chains interleaved
# baseline (speedup 1.0000x reference)
.LBB0_1119:
	s_lshl_b32 s2, s54, 4
	v_or_b32_e32 v18, s2, v104
	v_or_b32_e32 v32, s2, v144
	s_and_b64 vcc, exec, s[60:61]
	s_cbranch_vccz .Ls4_A
	s_cmp_eq_u32 s94, 1
	s_cbranch_scc1 .Ls4_C
	s_cmp_eq_u32 s94, 2
	s_cbranch_scc1 .Ls4_D
	v_add_u32_e32 v228, v25, v28
	v_add_u32_e32 v229, v25, v29
	v_lshrrev_b32_e32 v230, 3, v18
	v_mad_u32_u24 v231, v18, s96, 0
	v_xor_b32_e32 v232, v230, v108
	v_lshl_add_u32 v232, v232, 4, v231
	ds_read_b128 v[54:57], v228 offset:46080
	ds_read_b128 v[58:61], v232 offset:55296
	v_add_u32_e32 v233, 0x18c00, v231
	v_add_u32_e32 v234, v233, v106
	ds_read_b128 v[70:73], v228 offset:36864
	ds_read_b128 v[74:77], v234
	v_xor_b32_e32 v230, v230, v119
	v_lshl_add_u32 v230, v230, 4, v231
	ds_read_b128 v[62:65], v229 offset:46080
	ds_read_b128 v[66:69], v230 offset:55296
	v_add_u32_e32 v233, v233, v120
	ds_read_b128 v[78:81], v229 offset:36864
	ds_read_b128 v[82:85], v233
	v_lshrrev_b32_e32 v230, 3, v32
	v_mad_u32_u24 v231, v32, s96, 0
	v_xor_b32_e32 v232, v230, v108
	v_lshl_add_u32 v232, v232, 4, v231
	ds_read_b128 v[36:39], v232 offset:55296
	v_add_u32_e32 v233, 0x18c00, v231
	v_add_u32_e32 v234, v233, v106
	ds_read_b128 v[44:47], v234
	v_xor_b32_e32 v230, v230, v119
	v_lshl_add_u32 v230, v230, 4, v231
	ds_read_b128 v[40:43], v230 offset:55296
	v_add_u32_e32 v233, v233, v120
	ds_read_b128 v[48:51], v233
	s_waitcnt lgkmcnt(10)
	v_mfma_f32_16x16x32_bf16 v[100:103], v[54:57], v[58:61], 0
	s_waitcnt lgkmcnt(8)
	v_mfma_f32_16x16x32_bf16 v[194:197], v[70:73], v[74:77], 0
	s_waitcnt lgkmcnt(6)
	v_mfma_f32_16x16x32_bf16 v[100:103], v[62:65], v[66:69], v[100:103]
	s_waitcnt lgkmcnt(4)
	v_mfma_f32_16x16x32_bf16 v[194:197], v[78:81], v[82:85], v[194:197]
	s_waitcnt lgkmcnt(3)
	v_mfma_f32_16x16x32_bf16 v[248:251], v[54:57], v[36:39], 0
	s_waitcnt lgkmcnt(2)
	v_mfma_f32_16x16x32_bf16 v[252:255], v[70:73], v[44:47], 0
	s_waitcnt lgkmcnt(1)
	v_mfma_f32_16x16x32_bf16 v[248:251], v[62:65], v[40:43], v[248:251]
	s_waitcnt lgkmcnt(0)
	v_mfma_f32_16x16x32_bf16 v[252:255], v[78:81], v[48:51], v[252:255]
	s_nop 7
	v_sub_f32_e32 v14, v101, v195
	v_sub_f32_e32 v16, v100, v194
	v_cvt_pk_bf16_f32 v16, v16, v14
	v_sub_f32_e32 v14, v102, v196
	v_sub_f32_e32 v17, v103, v197
	v_sub_f32_e32 v33, v249, v253
	v_sub_f32_e32 v34, v248, v252
	v_sub_f32_e32 v18, v250, v254
	v_sub_f32_e32 v19, v251, v255
	v_cvt_pk_bf16_f32 v35, v34, v33
	s_branch .LBB0_1118
.Ls4_C:
	v_add_u32_e32 v228, v25, v28
	v_add_u32_e32 v229, v25, v29
	v_mad_u32_u24 v231, v18, s96, 0
	v_add_u32_e32 v231, 0x14400, v231
	v_add_u32_e32 v232, v231, v106
	ds_read_b128 v[54:57], v228 offset:55296
	ds_read_b128 v[58:61], v232
	v_add_u32_e32 v233, 0x18c00, v30
	v_mad_u32_u24 v234, v18, s85, v86
	v_lshlrev_b32_e32 v234, 1, v234
	v_add_u32_e32 v234, 0x12000, v234
	ds_read_b128 v[70:73], v233
	ds_read_b128 v[74:77], v234
	v_add_u32_e32 v232, v231, v120
	ds_read_b128 v[62:65], v229 offset:55296
	ds_read_b128 v[66:69], v232
	ds_read_b128 v[78:81], v233 offset:64
	ds_read_b128 v[82:85], v234 offset:64
	v_mad_u32_u24 v231, v32, s96, 0
	v_add_u32_e32 v231, 0x14400, v231
	v_add_u32_e32 v232, v231, v106
	ds_read_b128 v[36:39], v232
	v_mad_u32_u24 v234, v32, s85, v86
	v_lshlrev_b32_e32 v234, 1, v234
	v_add_u32_e32 v234, 0x12000, v234
	ds_read_b128 v[44:47], v234
	v_add_u32_e32 v232, v231, v120
	ds_read_b128 v[40:43], v232
	ds_read_b128 v[48:51], v234 offset:64
	s_waitcnt lgkmcnt(10)
	v_mfma_f32_16x16x32_bf16 v[100:103], v[54:57], v[58:61], 0
	s_waitcnt lgkmcnt(8)
	v_mfma_f32_16x16x32_bf16 v[194:197], v[70:73], v[74:77], 0
	s_waitcnt lgkmcnt(6)
	v_mfma_f32_16x16x32_bf16 v[100:103], v[62:65], v[66:69], v[100:103]
	s_waitcnt lgkmcnt(4)
	v_mfma_f32_16x16x32_bf16 v[194:197], v[78:81], v[82:85], v[194:197]
	s_waitcnt lgkmcnt(3)
	v_mfma_f32_16x16x32_bf16 v[248:251], v[54:57], v[36:39], 0
	s_waitcnt lgkmcnt(2)
	v_mfma_f32_16x16x32_bf16 v[252:255], v[70:73], v[44:47], 0
	s_waitcnt lgkmcnt(1)
	v_mfma_f32_16x16x32_bf16 v[248:251], v[62:65], v[40:43], v[248:251]
	s_waitcnt lgkmcnt(0)
	v_mfma_f32_16x16x32_bf16 v[252:255], v[78:81], v[48:51], v[252:255]
	s_nop 7
	v_sub_f32_e32 v14, v101, v195
	v_sub_f32_e32 v16, v100, v194
	v_cvt_pk_bf16_f32 v16, v16, v14
	v_sub_f32_e32 v14, v102, v196
	v_sub_f32_e32 v17, v103, v197
	v_sub_f32_e32 v33, v249, v253
	v_sub_f32_e32 v34, v248, v252
	v_sub_f32_e32 v18, v250, v254
	v_sub_f32_e32 v19, v251, v255
	v_cvt_pk_bf16_f32 v35, v34, v33
	s_branch .LBB0_1118
.Ls4_D:
	v_add_u32_e32 v228, v23, v106
	v_add_u32_e32 v229, v23, v120
	v_lshrrev_b32_e32 v230, 3, v18
	v_mad_u32_u24 v231, v18, s96, 0
	v_xor_b32_e32 v232, v230, v108
	v_lshl_add_u32 v232, v232, 4, v231
	ds_read_b128 v[54:57], v228
	ds_read_b128 v[58:61], v232 offset:36864
	v_lshrrev_b32_e32 v233, 3, v32
	v_mad_u32_u24 v234, v32, s96, 0
	v_xor_b32_e32 v232, v233, v108
	v_lshl_add_u32 v232, v232, 4, v234
	ds_read_b128 v[36:39], v232 offset:36864
	v_xor_b32_e32 v230, v230, v119
	v_lshl_add_u32 v230, v230, 4, v231
	ds_read_b128 v[62:65], v229
	ds_read_b128 v[66:69], v230 offset:36864
	v_xor_b32_e32 v233, v233, v119
	v_lshl_add_u32 v233, v233, 4, v234
	ds_read_b128 v[40:43], v233 offset:36864
	v_lshl_add_u32 v235, v18, 2, s47
	ds_read_b32 v236, v235
	ds_read_b32 v237, v235 offset:64
	s_waitcnt lgkmcnt(5)
	v_mfma_f32_16x16x32_bf16 v[100:103], v[54:57], v[58:61], 0
	v_mfma_f32_16x16x32_bf16 v[248:251], v[54:57], v[36:39], 0
	s_waitcnt lgkmcnt(2)
	v_mfma_f32_16x16x32_bf16 v[100:103], v[62:65], v[66:69], v[100:103]
	v_mfma_f32_16x16x32_bf16 v[248:251], v[62:65], v[40:43], v[248:251]
	s_waitcnt lgkmcnt(0)
	v_mul_f32_e32 v236, 0x3fb8aa3b, v236
	v_mul_f32_e32 v237, 0x3fb8aa3b, v237
	v_exp_f32_e32 v236, v236
	v_exp_f32_e32 v237, v237
	s_nop 7
	v_cmp_eq_u32_e32 vcc, v1, v18
	s_nop 1
	v_cndmask_b32_e32 v17, 0, v236, vcc
	v_cmp_eq_u32_e32 vcc, v22, v18
	s_nop 1
	v_cndmask_b32_e32 v16, 0, v236, vcc
	v_cmp_eq_u32_e32 vcc, v24, v18
	v_pk_add_f32 v[52:53], v[16:17], v[100:101] neg_lo:[0,1] neg_hi:[0,1]
	s_nop 0
	v_cndmask_b32_e32 v14, 0, v236, vcc
	v_cmp_eq_u32_e32 vcc, v15, v18
	v_sub_f32_e32 v14, v14, v102
	s_nop 0
	v_cndmask_b32_e32 v16, 0, v236, vcc
	v_sub_f32_e32 v17, v16, v103
	v_cvt_pk_bf16_f32 v16, v52, v53
	v_cmp_eq_u32_e32 vcc, v1, v32
	s_nop 1
	v_cndmask_b32_e32 v19, 0, v237, vcc
	v_cmp_eq_u32_e32 vcc, v22, v32
	s_nop 1
	v_cndmask_b32_e32 v18, 0, v237, vcc
	v_cmp_eq_u32_e32 vcc, v15, v32
	v_pk_add_f32 v[34:35], v[18:19], v[248:249] neg_lo:[0,1] neg_hi:[0,1]
	s_nop 0
	v_cndmask_b32_e32 v19, 0, v237, vcc
	v_cmp_eq_u32_e32 vcc, v24, v32
	v_cvt_pk_bf16_f32 v35, v34, v35
	s_nop 0
	v_cndmask_b32_e32 v18, 0, v237, vcc
	v_pk_add_f32 v[18:19], v[18:19], v[250:251] neg_lo:[0,1] neg_hi:[0,1]
	s_branch .LBB0_1118
.Ls4_A:
	v_add_u32_e32 v228, 0x16800, v30
	v_mad_u32_u24 v229, v18, s85, v86
	v_lshlrev_b32_e32 v229, 1, v229
	v_add_u32_e32 v229, 0x12000, v229
	ds_read_b128 v[54:57], v228
	ds_read_b128 v[58:61], v229
	v_mad_u32_u24 v230, v32, s85, v86
	v_lshlrev_b32_e32 v230, 1, v230
	v_add_u32_e32 v230, 0x12000, v230
	ds_read_b128 v[36:39], v230
	ds_read_b128 v[62:65], v228 offset:64
	ds_read_b128 v[66:69], v229 offset:64
	ds_read_b128 v[40:43], v230 offset:64
	v_mad_u32_u24 v231, v18, s85, v22
	v_lshlrev_b32_e32 v231, 1, v231
	ds_read_b64 v[232:233], v231 offset:9216
	v_mad_u32_u24 v231, v32, s85, v22
	v_lshlrev_b32_e32 v231, 1, v231
	ds_read_b64 v[234:235], v231 offset:9216
	s_waitcnt lgkmcnt(5)
	v_mfma_f32_16x16x32_bf16 v[100:103], v[54:57], v[58:61], 0
	v_mfma_f32_16x16x32_bf16 v[248:251], v[54:57], v[36:39], 0
	s_waitcnt lgkmcnt(2)
	v_mfma_f32_16x16x32_bf16 v[100:103], v[62:65], v[66:69], v[100:103]
	v_mfma_f32_16x16x32_bf16 v[248:251], v[62:65], v[40:43], v[248:251]
	s_waitcnt lgkmcnt(0)
	s_nop 7
	s_nop 1
	v_lshlrev_b32_e32 v14, 16, v232
	v_sub_f32_e32 v52, v14, v100
	v_and_b32_e32 v14, 0xffff0000, v232
	v_sub_f32_e32 v16, v14, v101
	v_lshlrev_b32_e32 v14, 16, v233
	v_and_b32_e32 v17, 0xffff0000, v233
	v_sub_f32_e32 v14, v14, v102
	v_sub_f32_e32 v17, v17, v103
	v_cvt_pk_bf16_f32 v16, v52, v16
	v_lshlrev_b32_e32 v31, 16, v234
	v_and_b32_e32 v18, 0xffff0000, v234
	v_sub_f32_e32 v31, v31, v248
	v_sub_f32_e32 v32, v18, v249
	v_lshlrev_b32_e32 v18, 16, v235
	v_and_b32_e32 v19, 0xffff0000, v235
	v_pk_add_f32 v[18:19], v[18:19], v[250:251] neg_lo:[0,1] neg_hi:[0,1]
	v_cvt_pk_bf16_f32 v35, v31, v32
	s_branch .LBB0_1118
